# in-proj GEMM: first K-iteration peeled with C=0 (no accumulator zeroing between tiles)
# speedup vs baseline: 1.0191x; 1.0191x over previous
; #define PG8_STAGE(bufoff, gbase, voff) do { _Pragma("unroll") for (int _i = 0; _i < 2; ++_i) \
;         __builtin_amdgcn_global_load_lds((const unsigned*)((const char*)(gbase) + (voff)[_i]), (PG8_LAS unsigned*)(lds + (bufoff) + ldsw + _i * 8192), 16, 0, 0); } while (0)
; #define PG8_LDA(dst, b, h) do { _Pragma("unroll") for (int m = 0; m < 4; ++m) _Pragma("unroll") for (int k = 0; k < 2; ++k) dst[m][k] = *(const PG8_LAS bf16x8*)(lds + PG8_SA(b, h) + aoff + m * 2048 + k * 1024); } while (0)
; #define PG8_WAIT_V(n) asm volatile("s_waitcnt vmcnt(" #n ")" ::: "memory")
; template <class Epi, class Sched>
; __device__ __forceinline__ void gemm_phase(PG8_LAS unsigned char* lds, const Gemm g, const Sched& S, const Epi& E) {
;     ...
;         const bool has_next = S.next(ui + 1, nxt);
;         const char* nA = has_next ? (const char*)g.A + (size_t)nxt.pm * tstep + (size_t)nxt.seg * SEGB : cA; const char* nB = has_next ? (const char*)g.Bt + (size_t)nxt.pn * tstep + (size_t)nxt.seg * SEGB : cB;
;         for (int t = 0; t < nt; t += 2) {
;             const bool last = (t == nt - 2);
;             const char* a1 = cA + (size_t)(t + 1) * kstep;
;             const char* a2 = last ? nA : cA + (size_t)(t + 2) * kstep; const char* b2 = last ? nB : cB + (size_t)(t + 2) * kstep;
;             const char* a3 = a2 + kstep; const char* b3 = b2 + kstep;
;             if (last && has_next) S.a_ready(nxt);
;             PG8_LDB(B0, 0, 0); PG8_SCHED; PG8_LDA(At, 0, 0); PG8_STAGE(PG8_SA(1, 1), a1 + hstep, voffA);
;             PG8_WAIT_L(8); PG8_BAR; PG8_WAIT_L(0); PG8_MMA(0, 0, At, B0); PG8_BAR; PG8_SCHED;
;             PG8_LDB(B1, 0, 1); PG8_STAGE(PG8_SB(0, 0), b2, voffB);
;             PG8_BAR; PG8_WAIT_L(0); PG8_MMA(0, 1, At, B1); PG8_BAR;
;             PG8_LDA(At, 0, 1); PG8_STAGE(PG8_SA(0, 0), a2, voffA);
;             PG8_BAR; PG8_WAIT_L(0); PG8_MMA(1, 0, At, B0); PG8_BAR; PG8_SCHED;
;             PG8_STAGE(PG8_SB(0, 1), b2 + hstep, voffB);
;             PG8_WAIT_V(6); PG8_BAR; PG8_MMA(1, 1, At, B1); PG8_BAR;
;     ...
;         if (!Epi::KEEP_ACC || cur.seg == 3)
; #pragma unroll
;         for (int a = 0; a < 2; ++a)
; #pragma unroll
;             for (int b = 0; b < 2; ++b)
; #pragma unroll
;                 for (int m = 0; m < 4; ++m)
; #pragma unroll
;                     for (int n = 0; n < 2; ++n) acc[a][b][m][n] = (f32x4){0.f, 0.f, 0.f, 0.f};
.LBB0_87:
	s_ashr_i32 s19, s18, 31
	v_cmp_lt_i64_e32 vcc, s[20:21], v[166:167]
	s_lshl_b64 s[20:21], s[18:19], 19
	s_add_u32 s20, s56, s20
	s_addc_u32 s21, s57, s21
	s_and_b64 s[38:39], vcc, exec
	s_cselect_b32 s19, s21, s41
	s_cselect_b32 s79, s20, s40
	s_ashr_i32 s7, s6, 31
	s_lshl_b64 s[38:39], s[6:7], 19
	s_add_u32 s38, s52, s38
	s_addc_u32 s39, s53, s39
	s_and_b64 s[50:51], vcc, exec
	s_cselect_b32 s7, s39, s11
	s_cselect_b32 s80, s38, s10
	s_add_u32 s40, s40, 0x40080
	s_addc_u32 s41, s41, 0
	s_add_u32 s81, s10, 0x100
	s_addc_u32 s82, s11, 0
	s_mov_b32 s83, -2
	s_add_u32 s10, s40, 0xfffc0080
	s_addc_u32 s11, s41, -1
	s_add_i32 s84, 0, 0x10000
	v_add_u32_e32 v156, s84, v141
	ds_read_b128 v[144:147], v156
	ds_read_b128 v[148:151], v156 offset:1024
	ds_read_b128 v[152:155], v156 offset:2048
	ds_read_b128 v[156:159], v156 offset:3072
	s_cmp_eq_u32 s83, 12
	s_cselect_b32 s51, s19, s11
	s_cselect_b32 s50, s79, s10
	s_cselect_b32 s11, s7, s82
	s_cselect_b32 s10, s80, s81
	v_lshl_add_u64 v[202:203], s[40:41], 0, v[136:137]
	s_add_i32 m0, s71, 0xc000
	ds_read_b128 v[160:163], v143
	ds_read_b128 v[174:177], v143 offset:1024
	ds_read_b128 v[178:181], v143 offset:2048
	ds_read_b128 v[182:185], v143 offset:3072
	ds_read_b128 v[186:189], v143 offset:4096
	ds_read_b128 v[190:193], v143 offset:5120
	ds_read_b128 v[194:197], v143 offset:6144
	ds_read_b128 v[198:201], v143 offset:7168
	global_load_lds_dwordx4 v[202:203], off
	v_lshl_add_u64 v[202:203], s[40:41], 0, v[138:139]
	s_add_i32 m0, s71, 0xe000
	s_nop 0
	global_load_lds_dwordx4 v[202:203], off
	s_waitcnt lgkmcnt(8)
	s_barrier
	s_waitcnt lgkmcnt(0)
	s_setprio 1
	s_waitcnt lgkmcnt(0)
	v_mfma_f32_16x16x32_bf16 v[126:129], v[144:147], v[160:163], 0
	v_mfma_f32_16x16x32_bf16 v[122:125], v[152:155], v[160:163], 0
	v_mfma_f32_16x16x32_bf16 v[118:121], v[144:147], v[178:181], 0
	v_mfma_f32_16x16x32_bf16 v[114:117], v[152:155], v[178:181], 0
	v_mfma_f32_16x16x32_bf16 v[102:105], v[144:147], v[186:189], 0
	v_mfma_f32_16x16x32_bf16 v[98:101], v[152:155], v[186:189], 0
	v_mfma_f32_16x16x32_bf16 v[86:89], v[144:147], v[194:197], 0
	v_mfma_f32_16x16x32_bf16 v[82:85], v[152:155], v[194:197], 0
	v_mfma_f32_16x16x32_bf16 v[126:129], v[148:151], v[174:177], v[126:129]
	v_mfma_f32_16x16x32_bf16 v[122:125], v[156:159], v[174:177], v[122:125]
	v_mfma_f32_16x16x32_bf16 v[118:121], v[148:151], v[182:185], v[118:121]
	v_mfma_f32_16x16x32_bf16 v[114:117], v[156:159], v[182:185], v[114:117]
	v_mfma_f32_16x16x32_bf16 v[102:105], v[148:151], v[190:193], v[102:105]
	v_mfma_f32_16x16x32_bf16 v[98:101], v[156:159], v[190:193], v[98:101]
	v_mfma_f32_16x16x32_bf16 v[86:89], v[148:151], v[198:201], v[86:89]
	v_mfma_f32_16x16x32_bf16 v[82:85], v[156:159], v[198:201], v[82:85]
	s_setprio 0
	s_barrier
	s_add_i32 s86, 0, 0x14000
	s_add_i32 s84, s84, s70
	v_add_u32_e32 v173, s86, v141
	v_lshl_add_u64 v[202:203], s[10:11], 0, v[0:1]
	s_mov_b32 m0, s84
	ds_read_b128 v[216:219], v173
	ds_read_b128 v[220:223], v173 offset:1024
	ds_read_b128 v[224:227], v173 offset:2048
	ds_read_b128 v[228:231], v173 offset:3072
	global_load_lds_dwordx4 v[202:203], off
	v_lshl_add_u64 v[232:233], s[10:11], 0, v[130:131]
	s_add_i32 m0, s84, 0x2000
	s_nop 0
	global_load_lds_dwordx4 v[232:233], off
	s_barrier
	s_waitcnt lgkmcnt(0)
	s_setprio 1
	s_waitcnt lgkmcnt(0)
	v_mfma_f32_16x16x32_bf16 v[110:113], v[216:219], v[160:163], 0
	v_mfma_f32_16x16x32_bf16 v[106:109], v[224:227], v[160:163], 0
	v_mfma_f32_16x16x32_bf16 v[94:97], v[216:219], v[178:181], 0
	v_mfma_f32_16x16x32_bf16 v[90:93], v[224:227], v[178:181], 0
	v_mfma_f32_16x16x32_bf16 v[78:81], v[216:219], v[186:189], 0
	v_mfma_f32_16x16x32_bf16 v[74:77], v[224:227], v[186:189], 0
	v_mfma_f32_16x16x32_bf16 v[70:73], v[216:219], v[194:197], 0
	v_mfma_f32_16x16x32_bf16 v[66:69], v[224:227], v[194:197], 0
	v_mfma_f32_16x16x32_bf16 v[110:113], v[220:223], v[174:177], v[110:113]
	v_mfma_f32_16x16x32_bf16 v[106:109], v[228:231], v[174:177], v[106:109]
	v_mfma_f32_16x16x32_bf16 v[94:97], v[220:223], v[182:185], v[94:97]
	v_mfma_f32_16x16x32_bf16 v[90:93], v[228:231], v[182:185], v[90:93]
	v_mfma_f32_16x16x32_bf16 v[78:81], v[220:223], v[190:193], v[78:81]
	v_mfma_f32_16x16x32_bf16 v[74:77], v[228:231], v[190:193], v[74:77]
	v_mfma_f32_16x16x32_bf16 v[70:73], v[220:223], v[198:201], v[70:73]
	v_mfma_f32_16x16x32_bf16 v[66:69], v[228:231], v[198:201], v[66:69]
	s_setprio 0
	s_mov_b32 m0, s71
	v_lshl_add_u64 v[234:235], s[50:51], 0, v[134:135]
	s_barrier
	ds_read_b128 v[160:163], v143 offset:16384
	ds_read_b128 v[174:177], v143 offset:17408
	ds_read_b128 v[178:181], v143 offset:18432
	ds_read_b128 v[182:185], v143 offset:19456
	ds_read_b128 v[186:189], v143 offset:20480
	ds_read_b128 v[190:193], v143 offset:21504
	ds_read_b128 v[194:197], v143 offset:22528
	ds_read_b128 v[198:201], v143 offset:23552
	global_load_lds_dwordx4 v[234:235], off
	v_lshl_add_u64 v[236:237], s[50:51], 0, v[132:133]
	s_mov_b32 m0, s72
	s_nop 0
	global_load_lds_dwordx4 v[236:237], off
	s_barrier
	s_waitcnt lgkmcnt(0)
	s_setprio 1
	s_waitcnt lgkmcnt(0)
	v_mfma_f32_16x16x32_bf16 v[62:65], v[144:147], v[160:163], 0
	v_mfma_f32_16x16x32_bf16 v[58:61], v[152:155], v[160:163], 0
	v_mfma_f32_16x16x32_bf16 v[54:57], v[144:147], v[178:181], 0
	v_mfma_f32_16x16x32_bf16 v[50:53], v[152:155], v[178:181], 0
	v_mfma_f32_16x16x32_bf16 v[38:41], v[144:147], v[186:189], 0
	v_mfma_f32_16x16x32_bf16 v[34:37], v[152:155], v[186:189], 0
	v_mfma_f32_16x16x32_bf16 v[22:25], v[144:147], v[194:197], 0
	v_mfma_f32_16x16x32_bf16 v[18:21], v[152:155], v[194:197], 0
	v_mfma_f32_16x16x32_bf16 v[62:65], v[148:151], v[174:177], v[62:65]
	v_mfma_f32_16x16x32_bf16 v[58:61], v[156:159], v[174:177], v[58:61]
	v_mfma_f32_16x16x32_bf16 v[54:57], v[148:151], v[182:185], v[54:57]
	v_mfma_f32_16x16x32_bf16 v[50:53], v[156:159], v[182:185], v[50:53]
	v_mfma_f32_16x16x32_bf16 v[38:41], v[148:151], v[190:193], v[38:41]
	v_mfma_f32_16x16x32_bf16 v[34:37], v[156:159], v[190:193], v[34:37]
	v_mfma_f32_16x16x32_bf16 v[22:25], v[148:151], v[198:201], v[22:25]
	v_mfma_f32_16x16x32_bf16 v[18:21], v[156:159], v[198:201], v[18:21]
	s_setprio 0
	s_barrier
; #define PG8_STAGE(bufoff, gbase, voff) do { _Pragma("unroll") for (int _i = 0; _i < 2; ++_i) \
;         __builtin_amdgcn_global_load_lds((const unsigned*)((const char*)(gbase) + (voff)[_i]), (PG8_LAS unsigned*)(lds + (bufoff) + ldsw + _i * 8192), 16, 0, 0); } while (0)
; #define PG8_LDA(dst, b, h) do { _Pragma("unroll") for (int m = 0; m < 4; ++m) _Pragma("unroll") for (int k = 0; k < 2; ++k) dst[m][k] = *(const PG8_LAS bf16x8*)(lds + PG8_SA(b, h) + aoff + m * 2048 + k * 1024); } while (0)
; #define PG8_LDB(dst, b, h) do { _Pragma("unroll") for (int n = 0; n < 2; ++n) _Pragma("unroll") for (int k = 0; k < 2; ++k) dst[n][k] = *(const PG8_LAS bf16x8*)(lds + PG8_SB(b, h) + boff + n * 2048 + k * 1024); } while (0)
; #define PG8_MMA(ai, bj, At, Bt) do { __builtin_amdgcn_s_setprio(1); _Pragma("unroll") for (int m = 0; m < 4; ++m) _Pragma("unroll") for (int n = 0; n < 2; ++n) _Pragma("unroll") for (int k = 0; k < 2; ++k) \
;         acc[ai][bj][m][n] = __builtin_amdgcn_mfma_f32_16x16x32_bf16(Bt[n][k], At[m][k], acc[ai][bj][m][n], 0, 0, 0); __builtin_amdgcn_s_setprio(0); } while (0)
; #define PG8_WAIT_V(n) asm volatile("s_waitcnt vmcnt(" #n ")" ::: "memory")
; #define PG8_WAIT_L(n) asm volatile("s_waitcnt lgkmcnt(" #n ")" ::: "memory")
; #define PG8_BAR __builtin_amdgcn_s_barrier()
; #define PG8_SCHED __builtin_amdgcn_sched_barrier(0)
; template <class Epi, class Sched>
; __device__ __forceinline__ void gemm_phase(PG8_LAS unsigned char* lds, const Gemm g, const Sched& S, const Epi& E) {
;     ...
;             PG8_WAIT_V(6); PG8_BAR; PG8_MMA(1, 1, At, B1); PG8_BAR;
;             PG8_LDB(B0, 1, 0); PG8_SCHED; PG8_LDA(At, 1, 0); PG8_STAGE(PG8_SA(0, 1), a2 + hstep, voffA);
;             PG8_WAIT_L(8); PG8_BAR; PG8_WAIT_L(0); PG8_MMA(0, 0, At, B0); PG8_BAR; PG8_SCHED;
;             PG8_LDB(B1, 1, 1); PG8_STAGE(PG8_SB(1, 0), b3, voffB);
;             PG8_BAR; PG8_WAIT_L(0); PG8_MMA(0, 1, At, B1); PG8_BAR;
;             PG8_LDA(At, 1, 1); PG8_STAGE(PG8_SA(1, 0), a3, voffA);
;             PG8_BAR; PG8_WAIT_L(0); PG8_MMA(1, 0, At, B0); PG8_BAR; PG8_SCHED;
	s_add_u32 s84, s10, 0x40000
	s_addc_u32 s85, s11, 0
	s_add_i32 s86, s86, s70
	v_lshl_add_u64 v[144:145], s[84:85], 0, v[0:1]
	s_mov_b32 m0, s86
	s_nop 0
	global_load_lds_dwordx4 v[144:145], off
	v_lshl_add_u64 v[144:145], s[84:85], 0, v[130:131]
	s_add_i32 m0, s86, 0x2000
	s_nop 0
	global_load_lds_dwordx4 v[144:145], off
	s_waitcnt vmcnt(6)
	s_barrier
	s_setprio 1
	v_mfma_f32_16x16x32_bf16 v[46:49], v[216:219], v[160:163], 0
	v_mfma_f32_16x16x32_bf16 v[42:45], v[224:227], v[160:163], 0
	v_mfma_f32_16x16x32_bf16 v[30:33], v[216:219], v[178:181], 0
	v_mfma_f32_16x16x32_bf16 v[26:29], v[224:227], v[178:181], 0
	v_mfma_f32_16x16x32_bf16 v[14:17], v[216:219], v[186:189], 0
	v_mfma_f32_16x16x32_bf16 v[10:13], v[224:227], v[186:189], 0
	v_mfma_f32_16x16x32_bf16 v[6:9], v[216:219], v[194:197], 0
	v_mfma_f32_16x16x32_bf16 v[2:5], v[224:227], v[194:197], 0
	v_mfma_f32_16x16x32_bf16 v[46:49], v[220:223], v[174:177], v[46:49]
	v_mfma_f32_16x16x32_bf16 v[42:45], v[228:231], v[174:177], v[42:45]
	v_mfma_f32_16x16x32_bf16 v[30:33], v[220:223], v[182:185], v[30:33]
	v_mfma_f32_16x16x32_bf16 v[26:29], v[228:231], v[182:185], v[26:29]
	v_mfma_f32_16x16x32_bf16 v[14:17], v[220:223], v[190:193], v[14:17]
	v_mfma_f32_16x16x32_bf16 v[10:13], v[228:231], v[190:193], v[10:13]
	v_mfma_f32_16x16x32_bf16 v[6:9], v[220:223], v[198:201], v[6:9]
	v_mfma_f32_16x16x32_bf16 v[2:5], v[228:231], v[198:201], v[2:5]
	s_setprio 0
	s_add_i32 s84, 0, 0x18000
	v_add_u32_e32 v156, s84, v141
	s_barrier
	ds_read_b128 v[144:147], v156
	ds_read_b128 v[148:151], v156 offset:1024
	ds_read_b128 v[152:155], v156 offset:2048
	ds_read_b128 v[156:159], v156 offset:3072
	s_add_u32 s50, s50, 0x40000
	s_addc_u32 s51, s51, 0
	s_mov_b32 m0, s73
	v_lshl_add_u64 v[216:217], s[50:51], 0, v[134:135]
	ds_read_b128 v[160:163], v143 offset:32768
	ds_read_b128 v[174:177], v143 offset:33792
	ds_read_b128 v[178:181], v143 offset:34816
	ds_read_b128 v[182:185], v143 offset:35840
	ds_read_b128 v[186:189], v143 offset:36864
	ds_read_b128 v[190:193], v143 offset:37888
	ds_read_b128 v[194:197], v143 offset:38912
	ds_read_b128 v[198:201], v143 offset:39936
	global_load_lds_dwordx4 v[216:217], off
	v_lshl_add_u64 v[216:217], s[50:51], 0, v[132:133]
	s_mov_b32 m0, s74
	s_nop 0
	global_load_lds_dwordx4 v[216:217], off
	s_waitcnt lgkmcnt(8)
	s_barrier
	s_waitcnt lgkmcnt(0)
	s_setprio 1
	s_waitcnt lgkmcnt(0)
	v_mfma_f32_16x16x32_bf16 v[126:129], v[144:147], v[160:163], v[126:129]
	v_mfma_f32_16x16x32_bf16 v[122:125], v[152:155], v[160:163], v[122:125]
	v_mfma_f32_16x16x32_bf16 v[118:121], v[144:147], v[178:181], v[118:121]
	v_mfma_f32_16x16x32_bf16 v[114:117], v[152:155], v[178:181], v[114:117]
	v_mfma_f32_16x16x32_bf16 v[102:105], v[144:147], v[186:189], v[102:105]
	v_mfma_f32_16x16x32_bf16 v[98:101], v[152:155], v[186:189], v[98:101]
	v_mfma_f32_16x16x32_bf16 v[86:89], v[144:147], v[194:197], v[86:89]
	v_mfma_f32_16x16x32_bf16 v[82:85], v[152:155], v[194:197], v[82:85]
	v_mfma_f32_16x16x32_bf16 v[126:129], v[148:151], v[174:177], v[126:129]
	v_mfma_f32_16x16x32_bf16 v[122:125], v[156:159], v[174:177], v[122:125]
	v_mfma_f32_16x16x32_bf16 v[118:121], v[148:151], v[182:185], v[118:121]
	v_mfma_f32_16x16x32_bf16 v[114:117], v[156:159], v[182:185], v[114:117]
	v_mfma_f32_16x16x32_bf16 v[102:105], v[148:151], v[190:193], v[102:105]
	v_mfma_f32_16x16x32_bf16 v[98:101], v[156:159], v[190:193], v[98:101]
	v_mfma_f32_16x16x32_bf16 v[86:89], v[148:151], v[198:201], v[86:89]
	v_mfma_f32_16x16x32_bf16 v[82:85], v[156:159], v[198:201], v[82:85]
	s_setprio 0
	s_barrier
	s_add_i32 s50, 0, 0x1c000
	s_add_i32 s51, s84, s70
	v_add_u32_e32 v173, s50, v141
	v_lshl_add_u64 v[202:203], v[202:203], 0, s[8:9]
	s_mov_b32 m0, s51
	ds_read_b128 v[216:219], v173
	ds_read_b128 v[220:223], v173 offset:1024
	ds_read_b128 v[224:227], v173 offset:2048
	ds_read_b128 v[228:231], v173 offset:3072
	global_load_lds_dwordx4 v[202:203], off
	v_lshl_add_u64 v[202:203], v[232:233], 0, s[8:9]
	s_add_i32 m0, s51, 0x2000
	s_nop 0
	global_load_lds_dwordx4 v[202:203], off
	s_barrier
; #define PG8_STAGE(bufoff, gbase, voff) do { _Pragma("unroll") for (int _i = 0; _i < 2; ++_i) \
;         __builtin_amdgcn_global_load_lds((const unsigned*)((const char*)(gbase) + (voff)[_i]), (PG8_LAS unsigned*)(lds + (bufoff) + ldsw + _i * 8192), 16, 0, 0); } while (0)
; #define PG8_LDA(dst, b, h) do { _Pragma("unroll") for (int m = 0; m < 4; ++m) _Pragma("unroll") for (int k = 0; k < 2; ++k) dst[m][k] = *(const PG8_LAS bf16x8*)(lds + PG8_SA(b, h) + aoff + m * 2048 + k * 1024); } while (0)
; #define PG8_MMA(ai, bj, At, Bt) do { __builtin_amdgcn_s_setprio(1); _Pragma("unroll") for (int m = 0; m < 4; ++m) _Pragma("unroll") for (int n = 0; n < 2; ++n) _Pragma("unroll") for (int k = 0; k < 2; ++k) \
;         acc[ai][bj][m][n] = __builtin_amdgcn_mfma_f32_16x16x32_bf16(Bt[n][k], At[m][k], acc[ai][bj][m][n], 0, 0, 0); __builtin_amdgcn_s_setprio(0); } while (0)
; #define PG8_WAIT_V(n) asm volatile("s_waitcnt vmcnt(" #n ")" ::: "memory")
; #define PG8_WAIT_L(n) asm volatile("s_waitcnt lgkmcnt(" #n ")" ::: "memory")
; #define PG8_BAR __builtin_amdgcn_s_barrier()
; #define PG8_SCHED __builtin_amdgcn_sched_barrier(0)
; template <class Epi, class Sched>
; __device__ __forceinline__ void gemm_phase(PG8_LAS unsigned char* lds, const Gemm g, const Sched& S, const Epi& E) {
;     ...
;             PG8_BAR; PG8_WAIT_L(0); PG8_MMA(0, 1, At, B1); PG8_BAR;
;             PG8_LDA(At, 1, 1); PG8_STAGE(PG8_SA(1, 0), a3, voffA);
;             PG8_BAR; PG8_WAIT_L(0); PG8_MMA(1, 0, At, B0); PG8_BAR; PG8_SCHED;
;             PG8_STAGE(PG8_SB(1, 1), b3 + hstep, voffB);
;             PG8_WAIT_V(6); PG8_BAR; PG8_MMA(1, 1, At, B1); PG8_BAR;
;         }
	s_waitcnt lgkmcnt(0)
	s_setprio 1
	s_waitcnt lgkmcnt(0)
	v_mfma_f32_16x16x32_bf16 v[110:113], v[216:219], v[160:163], v[110:113]
	v_mfma_f32_16x16x32_bf16 v[106:109], v[224:227], v[160:163], v[106:109]
	v_mfma_f32_16x16x32_bf16 v[94:97], v[216:219], v[178:181], v[94:97]
	v_mfma_f32_16x16x32_bf16 v[90:93], v[224:227], v[178:181], v[90:93]
	v_mfma_f32_16x16x32_bf16 v[78:81], v[216:219], v[186:189], v[78:81]
	v_mfma_f32_16x16x32_bf16 v[74:77], v[224:227], v[186:189], v[74:77]
	v_mfma_f32_16x16x32_bf16 v[70:73], v[216:219], v[194:197], v[70:73]
	v_mfma_f32_16x16x32_bf16 v[66:69], v[224:227], v[194:197], v[66:69]
	v_mfma_f32_16x16x32_bf16 v[110:113], v[220:223], v[174:177], v[110:113]
	v_mfma_f32_16x16x32_bf16 v[106:109], v[228:231], v[174:177], v[106:109]
	v_mfma_f32_16x16x32_bf16 v[94:97], v[220:223], v[182:185], v[94:97]
	v_mfma_f32_16x16x32_bf16 v[90:93], v[228:231], v[182:185], v[90:93]
	v_mfma_f32_16x16x32_bf16 v[78:81], v[220:223], v[190:193], v[78:81]
	v_mfma_f32_16x16x32_bf16 v[74:77], v[228:231], v[190:193], v[74:77]
	v_mfma_f32_16x16x32_bf16 v[70:73], v[220:223], v[198:201], v[70:73]
	v_mfma_f32_16x16x32_bf16 v[66:69], v[228:231], v[198:201], v[66:69]
	s_setprio 0
	s_mov_b32 m0, s75
	v_lshl_add_u64 v[202:203], v[234:235], 0, s[8:9]
	s_barrier
	ds_read_b128 v[160:163], v143 offset:49152
	ds_read_b128 v[174:177], v143 offset:50176
	ds_read_b128 v[178:181], v143 offset:51200
	ds_read_b128 v[182:185], v143 offset:52224
	ds_read_b128 v[186:189], v143 offset:53248
	ds_read_b128 v[190:193], v143 offset:54272
	ds_read_b128 v[194:197], v143 offset:55296
	ds_read_b128 v[198:201], v143 offset:56320
	global_load_lds_dwordx4 v[202:203], off
	v_lshl_add_u64 v[202:203], v[236:237], 0, s[8:9]
	s_mov_b32 m0, s76
	s_nop 0
	global_load_lds_dwordx4 v[202:203], off
	s_barrier
	s_waitcnt lgkmcnt(0)
	s_setprio 1
	s_waitcnt lgkmcnt(0)
	v_mfma_f32_16x16x32_bf16 v[62:65], v[144:147], v[160:163], v[62:65]
	v_mfma_f32_16x16x32_bf16 v[58:61], v[152:155], v[160:163], v[58:61]
	v_mfma_f32_16x16x32_bf16 v[54:57], v[144:147], v[178:181], v[54:57]
	v_mfma_f32_16x16x32_bf16 v[50:53], v[152:155], v[178:181], v[50:53]
	v_mfma_f32_16x16x32_bf16 v[38:41], v[144:147], v[186:189], v[38:41]
	v_mfma_f32_16x16x32_bf16 v[34:37], v[152:155], v[186:189], v[34:37]
	v_mfma_f32_16x16x32_bf16 v[22:25], v[144:147], v[194:197], v[22:25]
	v_mfma_f32_16x16x32_bf16 v[18:21], v[152:155], v[194:197], v[18:21]
	v_mfma_f32_16x16x32_bf16 v[62:65], v[148:151], v[174:177], v[62:65]
	v_mfma_f32_16x16x32_bf16 v[58:61], v[156:159], v[174:177], v[58:61]
	v_mfma_f32_16x16x32_bf16 v[54:57], v[148:151], v[182:185], v[54:57]
	v_mfma_f32_16x16x32_bf16 v[50:53], v[156:159], v[182:185], v[50:53]
	v_mfma_f32_16x16x32_bf16 v[38:41], v[148:151], v[190:193], v[38:41]
	v_mfma_f32_16x16x32_bf16 v[34:37], v[156:159], v[190:193], v[34:37]
	v_mfma_f32_16x16x32_bf16 v[22:25], v[148:151], v[198:201], v[22:25]
	v_mfma_f32_16x16x32_bf16 v[18:21], v[156:159], v[198:201], v[18:21]
	s_setprio 0
	s_barrier
	s_add_u32 s10, s10, 0x40080
	s_addc_u32 s11, s11, 0
	s_add_i32 s50, s50, s70
	v_lshl_add_u64 v[144:145], s[10:11], 0, v[0:1]
	s_mov_b32 m0, s50
	s_nop 0
	global_load_lds_dwordx4 v[144:145], off
	v_lshl_add_u64 v[144:145], s[10:11], 0, v[130:131]
	s_add_i32 m0, s50, 0x2000
	s_nop 0
	global_load_lds_dwordx4 v[144:145], off
	s_waitcnt vmcnt(6)
	s_barrier
	s_setprio 1
	v_mfma_f32_16x16x32_bf16 v[46:49], v[216:219], v[160:163], v[46:49]
	v_mfma_f32_16x16x32_bf16 v[42:45], v[224:227], v[160:163], v[42:45]
	v_mfma_f32_16x16x32_bf16 v[30:33], v[216:219], v[178:181], v[30:33]
	v_mfma_f32_16x16x32_bf16 v[26:29], v[224:227], v[178:181], v[26:29]
	v_mfma_f32_16x16x32_bf16 v[14:17], v[216:219], v[186:189], v[14:17]
	v_mfma_f32_16x16x32_bf16 v[10:13], v[224:227], v[186:189], v[10:13]
	v_mfma_f32_16x16x32_bf16 v[6:9], v[216:219], v[194:197], v[6:9]
	v_mfma_f32_16x16x32_bf16 v[2:5], v[224:227], v[194:197], v[2:5]
	v_mfma_f32_16x16x32_bf16 v[46:49], v[220:223], v[174:177], v[46:49]
	v_mfma_f32_16x16x32_bf16 v[42:45], v[228:231], v[174:177], v[42:45]
	v_mfma_f32_16x16x32_bf16 v[30:33], v[220:223], v[182:185], v[30:33]
	v_mfma_f32_16x16x32_bf16 v[26:29], v[228:231], v[182:185], v[26:29]
	v_mfma_f32_16x16x32_bf16 v[14:17], v[220:223], v[190:193], v[14:17]
	v_mfma_f32_16x16x32_bf16 v[10:13], v[228:231], v[190:193], v[10:13]
	v_mfma_f32_16x16x32_bf16 v[6:9], v[220:223], v[198:201], v[6:9]
	v_mfma_f32_16x16x32_bf16 v[2:5], v[228:231], v[198:201], v[2:5]
	s_setprio 0
	s_add_i32 s83, s83, 2
	s_add_u32 s40, s40, 0x100
	s_addc_u32 s41, s41, 0
	s_add_u32 s81, s81, 0x100
	s_addc_u32 s82, s82, 0
	s_cmp_gt_u32 s83, 13
	s_barrier
